# GU K-loop: 12 of 16 LDS-DMA loads use SGPR-base + 32-bit VGPR offset form (8 per-load 64-bit VALU address adds removed)
# speedup vs baseline: 1.0159x; 1.0036x over previous
; #define PG8_STAGE(bufoff, gbase, voff) do { _Pragma("unroll") for (int _i = 0; _i < 2; ++_i) \
;         __builtin_amdgcn_global_load_lds((const unsigned*)((const char*)(gbase) + (voff)[_i]), (LAS unsigned*)(lds + (bufoff) + ldsw + _i * 8192), 16, 0, 0); } while (0)
; #define PG8_LDA(dst, b, h) do { _Pragma("unroll") for (int m = 0; m < 4; ++m) _Pragma("unroll") for (int k = 0; k < 2; ++k) dst[m][k] = *(const LAS bf16x8*)(lds + PG8_SA(b, h) + aoff + m * 2048 + k * 1024); } while (0)
; #define PG8_LDB(dst, b, h) do { _Pragma("unroll") for (int n = 0; n < 2; ++n) _Pragma("unroll") for (int k = 0; k < 2; ++k) dst[n][k] = *(const LAS bf16x8*)(lds + PG8_SB(b, h) + boff + n * 2048 + k * 1024); } while (0)
; #define PG8_SCHED __builtin_amdgcn_sched_barrier(0)
; template <class Epi>
; DI void gemm_phase(LAS unsigned char* lds, const int tid, const Gemm g, const StaticOrder& S, const Epi& E) {
;     ...
;         for (int t = 0; t < nt; t += 2) {
;             const bool last = (t == nt - 2);
;             const char* a1 = cA + (size_t)(t + 1) * kstep;
;             const char* a2 = last ? nA : cA + (size_t)(t + 2) * kstep; const char* b2 = last ? nB : cB + (size_t)(t + 2) * kstep;
;             const char* a3 = a2 + kstep; const char* b3 = b2 + kstep;
;             PG8_LDB(B0, 0, 0); PG8_LDB(B1, 0, 1); PG8_SCHED; PG8_LDA(At, 0, 0); PG8_STAGE(PG8_SA(1, 1), a1 + hstepA, voffA);
.Lgu_rs_skip:
	s_add_u32 s36, s6, 0xfffc0080
	s_addc_u32 s37, s7, -1
	s_add_i32 s59, 0, 0x10000
	s_cmp_eq_u32 s58, 12
	s_cselect_b32 s41, s13, s37
	s_cselect_b32 s40, s52, s36
	v_add_u32_e32 v140, s59, v147
	s_cselect_b32 s37, s11, s57
	s_cselect_b32 s36, s53, s56
	s_add_i32 s62, 0, 0x14000
	ds_read_b128 v[156:159], v140
	ds_read_b128 v[160:163], v140 offset:1024
	ds_read_b128 v[164:167], v140 offset:2048
	ds_read_b128 v[168:171], v140 offset:3072
	v_add_u32_e32 v140, s62, v147
	ds_read_b128 v[172:175], v140
	ds_read_b128 v[176:179], v140 offset:1024
	ds_read_b128 v[180:183], v140 offset:2048
	ds_read_b128 v[184:187], v140 offset:3072
	s_add_i32 m0, s30, 0xc000
	ds_read_b128 v[188:191], v155
	ds_read_b128 v[192:195], v155 offset:1024
	ds_read_b128 v[196:199], v155 offset:2048
	ds_read_b128 v[208:211], v155 offset:3072
	ds_read_b128 v[212:215], v155 offset:4096
	ds_read_b128 v[216:219], v155 offset:5120
	ds_read_b128 v[220:223], v155 offset:6144
	ds_read_b128 v[224:227], v155 offset:7168
	global_load_lds_dwordx4 v136, s[6:7]
	s_add_i32 m0, s30, 0xe000
	s_nop 0
	global_load_lds_dwordx4 v138, s[6:7]
	s_cmp_eq_u32 s100, 0
	s_cbranch_scc1 .Lgu_ws1
	s_cmp_eq_u32 s100, 1
	s_cbranch_scc1 .Lgu_wr1
	s_waitcnt vmcnt(16)
	s_branch .Lgu_wq1

; #define PG8_STAGE(bufoff, gbase, voff) do { _Pragma("unroll") for (int _i = 0; _i < 2; ++_i) \
;         __builtin_amdgcn_global_load_lds((const unsigned*)((const char*)(gbase) + (voff)[_i]), (LAS unsigned*)(lds + (bufoff) + ldsw + _i * 8192), 16, 0, 0); } while (0)
; #define PG8_LDA(dst, b, h) do { _Pragma("unroll") for (int m = 0; m < 4; ++m) _Pragma("unroll") for (int k = 0; k < 2; ++k) dst[m][k] = *(const LAS bf16x8*)(lds + PG8_SA(b, h) + aoff + m * 2048 + k * 1024); } while (0)
; #define PG8_MMA(ai, bj, At, Bt) do { __builtin_amdgcn_s_setprio(1); _Pragma("unroll") for (int m = 0; m < 4; ++m) _Pragma("unroll") for (int n = 0; n < 2; ++n) _Pragma("unroll") for (int k = 0; k < 2; ++k) \
;         acc[ai][bj][m][n] = __builtin_amdgcn_mfma_f32_16x16x32_bf16(Bt[n][k], At[m][k], acc[ai][bj][m][n], 0, 0, 0); __builtin_amdgcn_s_setprio(0); } while (0)
; #define PG8_WAIT_V(n) asm volatile("s_waitcnt vmcnt(" #n ")" ::: "memory")
; #define PG8_WAIT_L(n) asm volatile("s_waitcnt lgkmcnt(" #n ")" ::: "memory")
; #define PG8_BAR __builtin_amdgcn_s_barrier()
; #define PG8_SCHED __builtin_amdgcn_sched_barrier(0)
; template <class Epi>
; DI void gemm_phase(LAS unsigned char* lds, const int tid, const Gemm g, const StaticOrder& S, const Epi& E) {
;     ...
;             PG8_WAIT_V(8); PG8_WAIT_L(0); PG8_BAR; PG8_MMA(0, 0, At, B0); PG8_MMA(0, 1, At, B1); PG8_BAR; PG8_SCHED;
;             PG8_LDA(At, 0, 1); PG8_STAGE(PG8_SB(0, 0), b2, voffB); PG8_STAGE(PG8_SB(0, 1), b2 + hstepB, voffB); PG8_STAGE(PG8_SA(0, 0), a2, voffA);
.Lgu_wd1:
	s_waitcnt lgkmcnt(0)
	s_barrier
	s_setprio 1
	s_waitcnt lgkmcnt(0)
	v_mfma_f32_16x16x32_bf16 v[126:129], v[156:159], v[188:191], v[126:129]
	v_mfma_f32_16x16x32_bf16 v[118:121], v[164:167], v[188:191], v[118:121]
	v_mfma_f32_16x16x32_bf16 v[110:113], v[156:159], v[196:199], v[110:113]
	v_mfma_f32_16x16x32_bf16 v[102:105], v[164:167], v[196:199], v[102:105]
	v_mfma_f32_16x16x32_bf16 v[94:97], v[156:159], v[212:215], v[94:97]
	v_mfma_f32_16x16x32_bf16 v[86:89], v[164:167], v[212:215], v[86:89]
	v_mfma_f32_16x16x32_bf16 v[78:81], v[156:159], v[220:223], v[78:81]
	v_mfma_f32_16x16x32_bf16 v[70:73], v[164:167], v[220:223], v[70:73]
	v_mfma_f32_16x16x32_bf16 v[126:129], v[160:163], v[192:195], v[126:129]
	v_mfma_f32_16x16x32_bf16 v[118:121], v[168:171], v[192:195], v[118:121]
	v_mfma_f32_16x16x32_bf16 v[110:113], v[160:163], v[208:211], v[110:113]
	v_mfma_f32_16x16x32_bf16 v[102:105], v[168:171], v[208:211], v[102:105]
	v_mfma_f32_16x16x32_bf16 v[94:97], v[160:163], v[216:219], v[94:97]
	v_mfma_f32_16x16x32_bf16 v[86:89], v[168:171], v[216:219], v[86:89]
	v_mfma_f32_16x16x32_bf16 v[78:81], v[160:163], v[224:227], v[78:81]
	v_mfma_f32_16x16x32_bf16 v[70:73], v[168:171], v[224:227], v[70:73]
	s_setprio 0
	s_setprio 1
	v_mfma_f32_16x16x32_bf16 v[122:125], v[172:175], v[188:191], v[122:125]
	v_mfma_f32_16x16x32_bf16 v[114:117], v[180:183], v[188:191], v[114:117]
	v_mfma_f32_16x16x32_bf16 v[106:109], v[172:175], v[196:199], v[106:109]
	v_mfma_f32_16x16x32_bf16 v[98:101], v[180:183], v[196:199], v[98:101]
	v_mfma_f32_16x16x32_bf16 v[90:93], v[172:175], v[212:215], v[90:93]
	v_mfma_f32_16x16x32_bf16 v[82:85], v[180:183], v[212:215], v[82:85]
	v_mfma_f32_16x16x32_bf16 v[74:77], v[172:175], v[220:223], v[74:77]
	v_mfma_f32_16x16x32_bf16 v[66:69], v[180:183], v[220:223], v[66:69]
	v_mfma_f32_16x16x32_bf16 v[122:125], v[176:179], v[192:195], v[122:125]
	v_mfma_f32_16x16x32_bf16 v[114:117], v[184:187], v[192:195], v[114:117]
	v_mfma_f32_16x16x32_bf16 v[106:109], v[176:179], v[208:211], v[106:109]
	v_mfma_f32_16x16x32_bf16 v[98:101], v[184:187], v[208:211], v[98:101]
	v_mfma_f32_16x16x32_bf16 v[90:93], v[176:179], v[216:219], v[90:93]
	v_mfma_f32_16x16x32_bf16 v[82:85], v[184:187], v[216:219], v[82:85]
	v_mfma_f32_16x16x32_bf16 v[74:77], v[176:179], v[224:227], v[74:77]
	v_mfma_f32_16x16x32_bf16 v[66:69], v[184:187], v[224:227], v[66:69]
	s_setprio 0
	s_barrier
	s_add_i32 s59, s59, s25
	v_lshl_add_u64 v[140:141], s[36:37], 0, v[0:1]
	s_mov_b32 m0, s59
	ds_read_b128 v[188:191], v155 offset:16384
	ds_read_b128 v[192:195], v155 offset:17408
	ds_read_b128 v[196:199], v155 offset:18432
	ds_read_b128 v[208:211], v155 offset:19456
	ds_read_b128 v[212:215], v155 offset:20480
	ds_read_b128 v[216:219], v155 offset:21504
	ds_read_b128 v[220:223], v155 offset:22528
	ds_read_b128 v[224:227], v155 offset:23552
	global_load_lds_dwordx4 v0, s[36:37]
	s_add_i32 m0, s59, 0x2000
	s_add_u32 s60, s36, 0x40000
	v_lshl_add_u64 v[148:149], s[36:37], 0, v[130:131]
	s_addc_u32 s61, s37, 0
	s_add_i32 s59, s62, s25
	global_load_lds_dwordx4 v130, s[36:37]
	s_mov_b32 m0, s59
	v_lshl_add_u64 v[202:203], s[40:41], 0, v[132:133]
	global_load_lds_dwordx4 v0, s[60:61]
	s_add_i32 m0, s59, 0x2000
	s_nop 0
	global_load_lds_dwordx4 v130, s[60:61]
	v_lshl_add_u64 v[200:201], s[40:41], 0, v[134:135]
	s_mov_b32 m0, s30
	s_nop 0
	global_load_lds_dwordx4 v134, s[40:41]
	s_mov_b32 m0, s31
	s_nop 0
	global_load_lds_dwordx4 v132, s[40:41]
	s_cmp_eq_u32 s100, 0
	s_cbranch_scc1 .Lgu_ws2
	s_cmp_eq_u32 s100, 1
	s_cbranch_scc1 .Lgu_wr2
	s_waitcnt vmcnt(16)
	s_branch .Lgu_wq2

; #define PG8_STAGE(bufoff, gbase, voff) do { _Pragma("unroll") for (int _i = 0; _i < 2; ++_i) \
;         __builtin_amdgcn_global_load_lds((const unsigned*)((const char*)(gbase) + (voff)[_i]), (LAS unsigned*)(lds + (bufoff) + ldsw + _i * 8192), 16, 0, 0); } while (0)
; #define PG8_LDA(dst, b, h) do { _Pragma("unroll") for (int m = 0; m < 4; ++m) _Pragma("unroll") for (int k = 0; k < 2; ++k) dst[m][k] = *(const LAS bf16x8*)(lds + PG8_SA(b, h) + aoff + m * 2048 + k * 1024); } while (0)
; #define PG8_LDB(dst, b, h) do { _Pragma("unroll") for (int n = 0; n < 2; ++n) _Pragma("unroll") for (int k = 0; k < 2; ++k) dst[n][k] = *(const LAS bf16x8*)(lds + PG8_SB(b, h) + boff + n * 2048 + k * 1024); } while (0)
; #define PG8_MMA(ai, bj, At, Bt) do { __builtin_amdgcn_s_setprio(1); _Pragma("unroll") for (int m = 0; m < 4; ++m) _Pragma("unroll") for (int n = 0; n < 2; ++n) _Pragma("unroll") for (int k = 0; k < 2; ++k) \
;         acc[ai][bj][m][n] = __builtin_amdgcn_mfma_f32_16x16x32_bf16(Bt[n][k], At[m][k], acc[ai][bj][m][n], 0, 0, 0); __builtin_amdgcn_s_setprio(0); } while (0)
; #define PG8_WAIT_V(n) asm volatile("s_waitcnt vmcnt(" #n ")" ::: "memory")
; #define PG8_WAIT_L(n) asm volatile("s_waitcnt lgkmcnt(" #n ")" ::: "memory")
; #define PG8_BAR __builtin_amdgcn_s_barrier()
; #define PG8_SCHED __builtin_amdgcn_sched_barrier(0)
; template <class Epi>
; DI void gemm_phase(LAS unsigned char* lds, const int tid, const Gemm g, const StaticOrder& S, const Epi& E) {
;     ...
;             PG8_WAIT_V(8); PG8_WAIT_L(0); PG8_BAR; PG8_MMA(1, 0, At, B0); PG8_MMA(1, 1, At, B1); PG8_BAR; PG8_SCHED;
;             PG8_LDB(B0, 1, 0); PG8_LDB(B1, 1, 1); PG8_SCHED; PG8_LDA(At, 1, 0); PG8_STAGE(PG8_SA(0, 1), a2 + hstepA, voffA);
;             PG8_WAIT_V(8); PG8_WAIT_L(0); PG8_BAR; PG8_MMA(0, 0, At, B0); PG8_MMA(0, 1, At, B1); PG8_BAR; PG8_SCHED;
.Lgu_wd2:
	s_waitcnt lgkmcnt(0)
	s_barrier
	s_setprio 1
	s_waitcnt lgkmcnt(0)
	v_mfma_f32_16x16x32_bf16 v[62:65], v[156:159], v[188:191], v[62:65]
	v_mfma_f32_16x16x32_bf16 v[54:57], v[164:167], v[188:191], v[54:57]
	v_mfma_f32_16x16x32_bf16 v[46:49], v[156:159], v[196:199], v[46:49]
	v_mfma_f32_16x16x32_bf16 v[38:41], v[164:167], v[196:199], v[38:41]
	v_mfma_f32_16x16x32_bf16 v[30:33], v[156:159], v[212:215], v[30:33]
	v_mfma_f32_16x16x32_bf16 v[22:25], v[164:167], v[212:215], v[22:25]
	v_mfma_f32_16x16x32_bf16 v[14:17], v[156:159], v[220:223], v[14:17]
	v_mfma_f32_16x16x32_bf16 v[6:9], v[164:167], v[220:223], v[6:9]
	v_mfma_f32_16x16x32_bf16 v[62:65], v[160:163], v[192:195], v[62:65]
	v_mfma_f32_16x16x32_bf16 v[54:57], v[168:171], v[192:195], v[54:57]
	v_mfma_f32_16x16x32_bf16 v[46:49], v[160:163], v[208:211], v[46:49]
	v_mfma_f32_16x16x32_bf16 v[38:41], v[168:171], v[208:211], v[38:41]
	v_mfma_f32_16x16x32_bf16 v[30:33], v[160:163], v[216:219], v[30:33]
	v_mfma_f32_16x16x32_bf16 v[22:25], v[168:171], v[216:219], v[22:25]
	v_mfma_f32_16x16x32_bf16 v[14:17], v[160:163], v[224:227], v[14:17]
	v_mfma_f32_16x16x32_bf16 v[6:9], v[168:171], v[224:227], v[6:9]
	s_setprio 0
	s_setprio 1
	v_mfma_f32_16x16x32_bf16 v[58:61], v[172:175], v[188:191], v[58:61]
	v_mfma_f32_16x16x32_bf16 v[50:53], v[180:183], v[188:191], v[50:53]
	v_mfma_f32_16x16x32_bf16 v[42:45], v[172:175], v[196:199], v[42:45]
	v_mfma_f32_16x16x32_bf16 v[34:37], v[180:183], v[196:199], v[34:37]
	v_mfma_f32_16x16x32_bf16 v[26:29], v[172:175], v[212:215], v[26:29]
	v_mfma_f32_16x16x32_bf16 v[18:21], v[180:183], v[212:215], v[18:21]
	v_mfma_f32_16x16x32_bf16 v[10:13], v[172:175], v[220:223], v[10:13]
	v_mfma_f32_16x16x32_bf16 v[2:5], v[180:183], v[220:223], v[2:5]
	v_mfma_f32_16x16x32_bf16 v[58:61], v[176:179], v[192:195], v[58:61]
	v_mfma_f32_16x16x32_bf16 v[50:53], v[184:187], v[192:195], v[50:53]
	v_mfma_f32_16x16x32_bf16 v[42:45], v[176:179], v[208:211], v[42:45]
	v_mfma_f32_16x16x32_bf16 v[34:37], v[184:187], v[208:211], v[34:37]
	v_mfma_f32_16x16x32_bf16 v[26:29], v[176:179], v[216:219], v[26:29]
	v_mfma_f32_16x16x32_bf16 v[18:21], v[184:187], v[216:219], v[18:21]
	v_mfma_f32_16x16x32_bf16 v[10:13], v[176:179], v[224:227], v[10:13]
	v_mfma_f32_16x16x32_bf16 v[2:5], v[184:187], v[224:227], v[2:5]
	s_setprio 0
	s_barrier
	s_add_i32 s59, 0, 0x18000
	v_add_u32_e32 v142, s59, v147
	s_add_i32 s60, 0, 0x1c000
	ds_read_b128 v[156:159], v142
	ds_read_b128 v[160:163], v142 offset:1024
	ds_read_b128 v[164:167], v142 offset:2048
	ds_read_b128 v[168:171], v142 offset:3072
	v_add_u32_e32 v142, s60, v147
	ds_read_b128 v[172:175], v142
	ds_read_b128 v[176:179], v142 offset:1024
	ds_read_b128 v[180:183], v142 offset:2048
	ds_read_b128 v[184:187], v142 offset:3072
	s_add_u32 s40, s40, 0x40000
	s_addc_u32 s41, s41, 0
	s_mov_b32 m0, s38
	ds_read_b128 v[188:191], v155 offset:32768
	ds_read_b128 v[192:195], v155 offset:33792
	ds_read_b128 v[196:199], v155 offset:34816
	ds_read_b128 v[208:211], v155 offset:35840
	ds_read_b128 v[212:215], v155 offset:36864
	ds_read_b128 v[216:219], v155 offset:37888
	ds_read_b128 v[220:223], v155 offset:38912
	ds_read_b128 v[224:227], v155 offset:39936
	global_load_lds_dwordx4 v134, s[40:41]
	s_mov_b32 m0, s39
	s_nop 0
	global_load_lds_dwordx4 v132, s[40:41]
	s_waitcnt vmcnt(8)
	s_waitcnt lgkmcnt(0)
	s_barrier
	s_setprio 1
	s_waitcnt lgkmcnt(0)
	v_mfma_f32_16x16x32_bf16 v[126:129], v[156:159], v[188:191], v[126:129]
	v_mfma_f32_16x16x32_bf16 v[118:121], v[164:167], v[188:191], v[118:121]
	v_mfma_f32_16x16x32_bf16 v[110:113], v[156:159], v[196:199], v[110:113]
	v_mfma_f32_16x16x32_bf16 v[102:105], v[164:167], v[196:199], v[102:105]
	v_mfma_f32_16x16x32_bf16 v[94:97], v[156:159], v[212:215], v[94:97]
	v_mfma_f32_16x16x32_bf16 v[86:89], v[164:167], v[212:215], v[86:89]
	v_mfma_f32_16x16x32_bf16 v[78:81], v[156:159], v[220:223], v[78:81]
	v_mfma_f32_16x16x32_bf16 v[70:73], v[164:167], v[220:223], v[70:73]
	v_mfma_f32_16x16x32_bf16 v[126:129], v[160:163], v[192:195], v[126:129]
	v_mfma_f32_16x16x32_bf16 v[118:121], v[168:171], v[192:195], v[118:121]
	v_mfma_f32_16x16x32_bf16 v[110:113], v[160:163], v[208:211], v[110:113]
	v_mfma_f32_16x16x32_bf16 v[102:105], v[168:171], v[208:211], v[102:105]
	v_mfma_f32_16x16x32_bf16 v[94:97], v[160:163], v[216:219], v[94:97]
	v_mfma_f32_16x16x32_bf16 v[86:89], v[168:171], v[216:219], v[86:89]
	v_mfma_f32_16x16x32_bf16 v[78:81], v[160:163], v[224:227], v[78:81]
	v_mfma_f32_16x16x32_bf16 v[70:73], v[168:171], v[224:227], v[70:73]
	s_setprio 0
	s_setprio 1
	v_mfma_f32_16x16x32_bf16 v[122:125], v[172:175], v[188:191], v[122:125]
	v_mfma_f32_16x16x32_bf16 v[114:117], v[180:183], v[188:191], v[114:117]
	v_mfma_f32_16x16x32_bf16 v[106:109], v[172:175], v[196:199], v[106:109]
	v_mfma_f32_16x16x32_bf16 v[98:101], v[180:183], v[196:199], v[98:101]
	v_mfma_f32_16x16x32_bf16 v[90:93], v[172:175], v[212:215], v[90:93]
	v_mfma_f32_16x16x32_bf16 v[82:85], v[180:183], v[212:215], v[82:85]
	v_mfma_f32_16x16x32_bf16 v[74:77], v[172:175], v[220:223], v[74:77]
	v_mfma_f32_16x16x32_bf16 v[66:69], v[180:183], v[220:223], v[66:69]
	v_mfma_f32_16x16x32_bf16 v[122:125], v[176:179], v[192:195], v[122:125]
	v_mfma_f32_16x16x32_bf16 v[114:117], v[184:187], v[192:195], v[114:117]
	v_mfma_f32_16x16x32_bf16 v[106:109], v[176:179], v[208:211], v[106:109]
	v_mfma_f32_16x16x32_bf16 v[98:101], v[184:187], v[208:211], v[98:101]
	v_mfma_f32_16x16x32_bf16 v[90:93], v[176:179], v[216:219], v[90:93]
	v_mfma_f32_16x16x32_bf16 v[82:85], v[184:187], v[216:219], v[82:85]
	v_mfma_f32_16x16x32_bf16 v[74:77], v[176:179], v[224:227], v[74:77]
	v_mfma_f32_16x16x32_bf16 v[66:69], v[184:187], v[224:227], v[66:69]
	s_setprio 0
	s_barrier
; #define PG8_STAGE(bufoff, gbase, voff) do { _Pragma("unroll") for (int _i = 0; _i < 2; ++_i) \
;         __builtin_amdgcn_global_load_lds((const unsigned*)((const char*)(gbase) + (voff)[_i]), (LAS unsigned*)(lds + (bufoff) + ldsw + _i * 8192), 16, 0, 0); } while (0)
; #define PG8_LDA(dst, b, h) do { _Pragma("unroll") for (int m = 0; m < 4; ++m) _Pragma("unroll") for (int k = 0; k < 2; ++k) dst[m][k] = *(const LAS bf16x8*)(lds + PG8_SA(b, h) + aoff + m * 2048 + k * 1024); } while (0)
; #define PG8_MMA(ai, bj, At, Bt) do { __builtin_amdgcn_s_setprio(1); _Pragma("unroll") for (int m = 0; m < 4; ++m) _Pragma("unroll") for (int n = 0; n < 2; ++n) _Pragma("unroll") for (int k = 0; k < 2; ++k) \
;         acc[ai][bj][m][n] = __builtin_amdgcn_mfma_f32_16x16x32_bf16(Bt[n][k], At[m][k], acc[ai][bj][m][n], 0, 0, 0); __builtin_amdgcn_s_setprio(0); } while (0)
; #define PG8_WAIT_V(n) asm volatile("s_waitcnt vmcnt(" #n ")" ::: "memory")
; #define PG8_WAIT_L(n) asm volatile("s_waitcnt lgkmcnt(" #n ")" ::: "memory")
; #define PG8_BAR __builtin_amdgcn_s_barrier()
; #define PG8_SCHED __builtin_amdgcn_sched_barrier(0)
; template <class Epi>
; DI void gemm_phase(LAS unsigned char* lds, const int tid, const Gemm g, const StaticOrder& S, const Epi& E) {
;     ...
;             PG8_LDA(At, 1, 1); PG8_STAGE(PG8_SB(1, 0), b3, voffB); PG8_STAGE(PG8_SB(1, 1), b3 + hstepB, voffB); PG8_STAGE(PG8_SA(1, 0), a3, voffA);
;             PG8_WAIT_V(8); PG8_WAIT_L(0); PG8_BAR; PG8_MMA(1, 0, At, B0); PG8_MMA(1, 1, At, B1); PG8_BAR; PG8_SCHED;
;         }
;         if (wr == 0) PG8_BAR;
	s_add_i32 s40, s59, s25
	v_lshl_add_u64 v[140:141], v[140:141], 0, s[54:55]
	s_mov_b32 m0, s40
	ds_read_b128 v[188:191], v155 offset:49152
	ds_read_b128 v[192:195], v155 offset:50176
	ds_read_b128 v[196:199], v155 offset:51200
	ds_read_b128 v[208:211], v155 offset:52224
	ds_read_b128 v[212:215], v155 offset:53248
	ds_read_b128 v[216:219], v155 offset:54272
	ds_read_b128 v[220:223], v155 offset:55296
	ds_read_b128 v[224:227], v155 offset:56320
	global_load_lds_dwordx4 v[140:141], off
	s_add_i32 m0, s40, 0x2000
	s_add_u32 s36, s36, 0x40080
	v_lshl_add_u64 v[140:141], v[148:149], 0, s[54:55]
	s_addc_u32 s37, s37, 0
	s_add_i32 s40, s60, s25
	global_load_lds_dwordx4 v[140:141], off
	s_mov_b32 m0, s40
	s_nop 0
	global_load_lds_dwordx4 v0, s[36:37]
	s_add_i32 m0, s40, 0x2000
	s_nop 0
	global_load_lds_dwordx4 v130, s[36:37]
	v_lshl_add_u64 v[140:141], v[200:201], 0, s[54:55]
	s_mov_b32 m0, s42
	s_nop 0
	global_load_lds_dwordx4 v[140:141], off
	v_lshl_add_u64 v[140:141], v[202:203], 0, s[54:55]
	s_mov_b32 m0, s43
	s_nop 0
	global_load_lds_dwordx4 v[140:141], off
	s_waitcnt vmcnt(8)
	s_waitcnt lgkmcnt(0)
	s_barrier
	s_setprio 1
	s_waitcnt lgkmcnt(0)
	v_mfma_f32_16x16x32_bf16 v[62:65], v[156:159], v[188:191], v[62:65]
	v_mfma_f32_16x16x32_bf16 v[54:57], v[164:167], v[188:191], v[54:57]
	v_mfma_f32_16x16x32_bf16 v[46:49], v[156:159], v[196:199], v[46:49]
	v_mfma_f32_16x16x32_bf16 v[38:41], v[164:167], v[196:199], v[38:41]
	v_mfma_f32_16x16x32_bf16 v[30:33], v[156:159], v[212:215], v[30:33]
	v_mfma_f32_16x16x32_bf16 v[22:25], v[164:167], v[212:215], v[22:25]
	v_mfma_f32_16x16x32_bf16 v[14:17], v[156:159], v[220:223], v[14:17]
	v_mfma_f32_16x16x32_bf16 v[6:9], v[164:167], v[220:223], v[6:9]
	v_mfma_f32_16x16x32_bf16 v[62:65], v[160:163], v[192:195], v[62:65]
	v_mfma_f32_16x16x32_bf16 v[54:57], v[168:171], v[192:195], v[54:57]
	v_mfma_f32_16x16x32_bf16 v[46:49], v[160:163], v[208:211], v[46:49]
	v_mfma_f32_16x16x32_bf16 v[38:41], v[168:171], v[208:211], v[38:41]
	v_mfma_f32_16x16x32_bf16 v[30:33], v[160:163], v[216:219], v[30:33]
	v_mfma_f32_16x16x32_bf16 v[22:25], v[168:171], v[216:219], v[22:25]
	v_mfma_f32_16x16x32_bf16 v[14:17], v[160:163], v[224:227], v[14:17]
	v_mfma_f32_16x16x32_bf16 v[6:9], v[168:171], v[224:227], v[6:9]
	s_setprio 0
	s_setprio 1
	v_mfma_f32_16x16x32_bf16 v[58:61], v[172:175], v[188:191], v[58:61]
	v_mfma_f32_16x16x32_bf16 v[50:53], v[180:183], v[188:191], v[50:53]
	v_mfma_f32_16x16x32_bf16 v[42:45], v[172:175], v[196:199], v[42:45]
	v_mfma_f32_16x16x32_bf16 v[34:37], v[180:183], v[196:199], v[34:37]
	v_mfma_f32_16x16x32_bf16 v[26:29], v[172:175], v[212:215], v[26:29]
	v_mfma_f32_16x16x32_bf16 v[18:21], v[180:183], v[212:215], v[18:21]
	v_mfma_f32_16x16x32_bf16 v[10:13], v[172:175], v[220:223], v[10:13]
	v_mfma_f32_16x16x32_bf16 v[2:5], v[180:183], v[220:223], v[2:5]
	v_mfma_f32_16x16x32_bf16 v[58:61], v[176:179], v[192:195], v[58:61]
	v_mfma_f32_16x16x32_bf16 v[50:53], v[184:187], v[192:195], v[50:53]
	v_mfma_f32_16x16x32_bf16 v[42:45], v[176:179], v[208:211], v[42:45]
	v_mfma_f32_16x16x32_bf16 v[34:37], v[184:187], v[208:211], v[34:37]
	v_mfma_f32_16x16x32_bf16 v[26:29], v[176:179], v[216:219], v[26:29]
	v_mfma_f32_16x16x32_bf16 v[18:21], v[184:187], v[216:219], v[18:21]
	v_mfma_f32_16x16x32_bf16 v[10:13], v[176:179], v[224:227], v[10:13]
	v_mfma_f32_16x16x32_bf16 v[2:5], v[184:187], v[224:227], v[2:5]
	s_setprio 0
	s_barrier
	s_add_i32 s58, s58, 2
	s_add_u32 s6, s6, 0x100
	s_addc_u32 s7, s7, 0
	s_add_u32 s56, s56, 0x100
	s_addc_u32 s57, s57, 0
	s_cmp_gt_u32 s58, 13
	s_cbranch_scc0 .LBB0_667
	s_and_b64 vcc, exec, s[8:9]
	s_cbranch_vccz .LBB0_670
	s_barrier
